# stick-breaking loop: V fragment LDS reads issued right after the QK MFMAs (into the freed K fragment registers)
# speedup vs baseline: 1.0009x; 1.0009x over previous
; #define LAS __attribute__((address_space(3)))
; #define MFMA32(a, b, c) __builtin_amdgcn_mfma_f32_32x32x16_bf16((a), (b), (c), 0, 0, 0)
; __device__ __forceinline__ void sb_unit(int b, int h, int qb, const bf16* U, const bf16* VT, bf16* Y, unsigned char* lds, int wid, int lane, int& res_lo, int& res_hi) {
;     ...
;         for (int t = (top < mytile ? top : mytile); t >= lo && alive; --t) {
;             const LAS unsigned char* Kb = kfp + (t & 7) * 16384; const LAS unsigned char* Vb = vfp + (t & 7) * 16384;
;             f32x16 y0 = f32x16{}, y1 = f32x16{};
; #pragma unroll
;             for (int ks = 0; ks < 4; ++ks) { const bf16x8 a0 = *(const LAS bf16x8*)(Kb + kofs[ks]), a1 = *(const LAS bf16x8*)(Kb + 4096 + kofs[ks]); y0 = MFMA32(a0, qf[ks], y0); y1 = MFMA32(a1, qf[ks], y1); }
; #pragma unroll
;             for (int r = 0; r < 16; ++r) { y0[r] = fminf(y0[r], 100.f); y1[r] = fminf(y1[r], 100.f); }
;             if (t == mytile) {
;                 int tqm = tq - 64 * t - 8 * hi; asm volatile("" : "+v"(tqm));
; #pragma unroll
;                 for (int r = 0; r < 16; ++r) { const int key = 16 * (r >> 3) + (r & 7); if (key >= tqm) y0[r] = -INFINITY; if (key + 32 >= tqm) y1[r] = -INFINITY; }
;             }
;     ...
; #pragma unroll
;             for (int db = 0; db < 2; ++db)
; #pragma unroll
;                 for (int kk = 0; kk < 4; ++kk) { const bf16x8 vf = *(const LAS bf16x8*)(Vb + db * 4096 + vofs[kk]); o[db] = MFMA32(vf, pk[kk], o[db]); }
.LBB0_726:
	s_and_b32 s69, s82, 0x1c000
	s_cmp_lg_u32 s96, s89
	s_waitcnt lgkmcnt(7)
	v_mfma_f32_32x32x16_bf16 v[64:79], v[212:215], v[100:103], 0
	s_waitcnt lgkmcnt(6)
	v_mfma_f32_32x32x16_bf16 v[80:95], v[216:219], v[100:103], 0
	s_waitcnt lgkmcnt(5)
	v_mfma_f32_32x32x16_bf16 v[64:79], v[220:223], v[104:107], v[64:79]
	s_waitcnt lgkmcnt(4)
	v_mfma_f32_32x32x16_bf16 v[80:95], v[224:227], v[104:107], v[80:95]
	s_waitcnt lgkmcnt(3)
	v_mfma_f32_32x32x16_bf16 v[64:79], v[228:231], v[108:111], v[64:79]
	s_waitcnt lgkmcnt(2)
	v_mfma_f32_32x32x16_bf16 v[80:95], v[232:235], v[108:111], v[80:95]
	s_waitcnt lgkmcnt(1)
	v_mfma_f32_32x32x16_bf16 v[64:79], v[236:239], v[112:115], v[64:79]
	s_waitcnt lgkmcnt(0)
	v_mfma_f32_32x32x16_bf16 v[80:95], v[240:243], v[112:115], v[80:95]
	v_add_u32_e32 v244, s69, v155
	v_add_u32_e32 v245, v244, v147
	v_add_u32_e32 v246, v244, v149
	v_add_u32_e32 v247, v244, v151
	v_add_u32_e32 v248, v244, v153
	ds_read_b128 v[212:215], v245 offset:8192
	ds_read_b128 v[216:219], v245 offset:12288
	ds_read_b128 v[220:223], v246 offset:8192
	ds_read_b128 v[224:227], v246 offset:12288
	ds_read_b128 v[228:231], v247 offset:8192
	ds_read_b128 v[232:235], v247 offset:12288
	ds_read_b128 v[236:239], v248 offset:8192
	ds_read_b128 v[240:243], v248 offset:12288
	v_min_f32_e32 v0, 0x42c80000, v64
	v_min_f32_e32 v3, 0x42c80000, v65
	v_min_f32_e32 v4, 0x42c80000, v66
	v_min_f32_e32 v7, 0x42c80000, v67
	v_min_f32_e32 v9, 0x42c80000, v68
	v_min_f32_e32 v12, 0x42c80000, v69
	v_min_f32_e32 v13, 0x42c80000, v70
	v_min_f32_e32 v15, 0x42c80000, v71
	v_min_f32_e32 v157, 0x42c80000, v73
	v_min_f32_e32 v159, 0x42c80000, v74
	v_min_f32_e32 v161, 0x42c80000, v75
	v_min_f32_e32 v164, 0x42c80000, v76
	v_min_f32_e32 v165, 0x42c80000, v77
	v_min_f32_e32 v167, 0x42c80000, v78
	v_min_f32_e32 v169, 0x42c80000, v79
	v_min_f32_e32 v2, 0x42c80000, v80
	v_min_f32_e32 v5, 0x42c80000, v81
	v_min_f32_e32 v81, 0x42c80000, v72
	v_min_f32_e32 v6, 0x42c80000, v82
	v_min_f32_e32 v8, 0x42c80000, v83
	v_min_f32_e32 v10, 0x42c80000, v84
	v_min_f32_e32 v11, 0x42c80000, v85
	v_min_f32_e32 v14, 0x42c80000, v86
	v_min_f32_e32 v80, 0x42c80000, v87
	v_min_f32_e32 v82, 0x42c80000, v88
	v_min_f32_e32 v158, 0x42c80000, v89
	v_min_f32_e32 v160, 0x42c80000, v90
	v_min_f32_e32 v162, 0x42c80000, v91
	v_min_f32_e32 v163, 0x42c80000, v92
	v_min_f32_e32 v166, 0x42c80000, v93
	v_min_f32_e32 v168, 0x42c80000, v94
	v_min_f32_e32 v170, 0x42c80000, v95
	s_cbranch_scc1 .LBB0_728
	v_mov_b32_e32 v64, v156
	s_nop 0
	v_cmp_lt_i32_e64 s[60:61], 22, v64
	v_cmp_lt_i32_e64 s[64:65], 23, v64
	v_cmp_lt_i32_e64 s[58:59], 21, v64
	s_or_b64 s[60:61], s[64:65], s[60:61]
	v_cmp_lt_i32_e64 s[56:57], 20, v64
	s_or_b64 s[58:59], s[60:61], s[58:59]
	v_cmp_lt_i32_e64 s[54:55], 19, v64
	s_or_b64 s[56:57], s[58:59], s[56:57]
	v_cmp_lt_i32_e64 s[52:53], 18, v64
	s_or_b64 s[54:55], s[56:57], s[54:55]
	v_cmp_lt_i32_e64 s[50:51], 17, v64
	s_or_b64 s[52:53], s[54:55], s[52:53]
	v_cmp_lt_i32_e64 s[48:49], 16, v64
	s_or_b64 s[50:51], s[52:53], s[50:51]
	v_cmp_lt_i32_e64 s[46:47], 7, v64
	s_or_b64 s[48:49], s[50:51], s[48:49]
	v_cmp_lt_i32_e64 s[44:45], 6, v64
	s_or_b64 s[46:47], s[48:49], s[46:47]
	v_cmp_lt_i32_e64 s[42:43], 5, v64
	s_or_b64 s[44:45], s[46:47], s[44:45]
	v_cmp_lt_i32_e64 s[40:41], 4, v64
	s_or_b64 s[42:43], s[44:45], s[42:43]
	v_cmp_lt_i32_e64 s[38:39], 3, v64
	s_or_b64 s[40:41], s[42:43], s[40:41]
	v_cmp_lt_i32_e64 s[36:37], 2, v64
	s_or_b64 s[38:39], s[40:41], s[38:39]
	v_cmp_lt_i32_e64 s[34:35], 1, v64
	s_or_b64 s[36:37], s[38:39], s[36:37]
	v_cmp_lt_i32_e64 s[30:31], 0, v64
	s_or_b64 s[34:35], s[36:37], s[34:35]
	s_or_b64 s[30:31], s[34:35], s[30:31]
	v_cmp_lt_i32_e64 s[62:63], 54, v64
	v_cndmask_b32_e64 v0, v145, v0, s[30:31]
	v_cmp_lt_i32_e64 s[30:31], 55, v64
	v_cmp_lt_i32_e64 s[28:29], 53, v64
	v_cmp_lt_i32_e64 s[26:27], 52, v64
	v_cndmask_b32_e64 v170, v145, v170, s[30:31]
	s_or_b64 s[30:31], s[30:31], s[62:63]
	s_or_b64 s[28:29], s[30:31], s[28:29]
	v_cmp_lt_i32_e64 s[24:25], 51, v64
	s_or_b64 s[26:27], s[28:29], s[26:27]
	v_cmp_lt_i32_e64 s[22:23], 50, v64
	s_or_b64 s[24:25], s[26:27], s[24:25]
	v_cmp_lt_i32_e64 s[20:21], 49, v64
	s_or_b64 s[22:23], s[24:25], s[22:23]
	v_cmp_lt_i32_e64 s[18:19], 48, v64
	s_or_b64 s[20:21], s[22:23], s[20:21]
	v_cmp_lt_i32_e64 s[16:17], 39, v64
	s_or_b64 s[18:19], s[20:21], s[18:19]
	v_cmp_lt_i32_e64 s[14:15], 38, v64
	s_or_b64 s[16:17], s[18:19], s[16:17]
	v_cmp_lt_i32_e64 s[12:13], 37, v64
	s_or_b64 s[14:15], s[16:17], s[14:15]
	v_cmp_lt_i32_e64 s[10:11], 36, v64
	s_or_b64 s[12:13], s[14:15], s[12:13]
	v_cmp_lt_i32_e64 s[8:9], 35, v64
	s_or_b64 s[10:11], s[12:13], s[10:11]
	v_cmp_lt_i32_e64 s[6:7], 34, v64
	s_or_b64 s[8:9], s[10:11], s[8:9]
	v_cmp_lt_i32_e64 s[2:3], 33, v64
	s_or_b64 s[6:7], s[8:9], s[6:7]
	v_cmp_lt_i32_e32 vcc, 32, v64
	s_or_b64 s[2:3], s[6:7], s[2:3]
	s_or_b64 vcc, s[2:3], vcc
	v_cndmask_b32_e64 v169, v145, v169, s[64:65]
	v_cndmask_b32_e64 v167, v145, v167, s[60:61]
	v_cndmask_b32_e64 v165, v145, v165, s[58:59]
	v_cndmask_b32_e64 v164, v145, v164, s[56:57]
	v_cndmask_b32_e64 v161, v145, v161, s[54:55]
	v_cndmask_b32_e64 v159, v145, v159, s[52:53]
	v_cndmask_b32_e64 v157, v145, v157, s[50:51]
	v_cndmask_b32_e64 v81, v145, v81, s[48:49]
	v_cndmask_b32_e64 v15, v145, v15, s[46:47]
	v_cndmask_b32_e64 v13, v145, v13, s[44:45]
	v_cndmask_b32_e64 v12, v145, v12, s[42:43]
	v_cndmask_b32_e64 v9, v145, v9, s[40:41]
	v_cndmask_b32_e64 v7, v145, v7, s[38:39]
	v_cndmask_b32_e64 v4, v145, v4, s[36:37]
	v_cndmask_b32_e64 v3, v145, v3, s[34:35]
	v_cndmask_b32_e64 v168, v145, v168, s[30:31]
	v_cndmask_b32_e64 v166, v145, v166, s[28:29]
	v_cndmask_b32_e64 v163, v145, v163, s[26:27]
	v_cndmask_b32_e64 v162, v145, v162, s[24:25]
	v_cndmask_b32_e64 v160, v145, v160, s[22:23]
	v_cndmask_b32_e64 v158, v145, v158, s[20:21]
	v_cndmask_b32_e64 v82, v145, v82, s[18:19]
	v_cndmask_b32_e64 v80, v145, v80, s[16:17]
	v_cndmask_b32_e64 v14, v145, v14, s[14:15]
	v_cndmask_b32_e64 v11, v145, v11, s[12:13]
	v_cndmask_b32_e64 v10, v145, v10, s[10:11]
	v_cndmask_b32_e64 v8, v145, v8, s[8:9]
	v_cndmask_b32_e64 v6, v145, v6, s[6:7]
	v_cndmask_b32_e64 v5, v145, v5, s[2:3]
	v_cndmask_b32_e32 v2, v145, v2, vcc
; #define LAS __attribute__((address_space(3)))
; #define MFMA32(a, b, c) __builtin_amdgcn_mfma_f32_32x32x16_bf16((a), (b), (c), 0, 0, 0)
; __device__ __forceinline__ void sb_unit(int b, int h, int qb, const bf16* U, const bf16* VT, bf16* Y, unsigned char* lds, int wid, int lane, int& res_lo, int& res_hi) {
;     ...
;             f32x16 l0, l1;
; #pragma unroll
;             for (int r = 0; r < 16; ++r) { l0[r] = __builtin_amdgcn_logf(1.f + __builtin_amdgcn_exp2f(y0[r])); l1[r] = __builtin_amdgcn_logf(1.f + __builtin_amdgcn_exp2f(y1[r])); }
;             bf16x8 lb[4]; lb[0] = pack8(l0, 0); lb[1] = pack8(l0, 8); lb[2] = pack8(l1, 0); lb[3] = pack8(l1, 8);
; #pragma unroll
;             for (int r = 0; r < 16; ++r) { y0[r] -= l0[r]; y1[r] -= l1[r]; }
;             f32x16 X = MFMA32(JN, lb[2], C); X = MFMA32(JN, lb[3], X);
;             f32x16 f1 = MFMA32(TM[0], lb[2], C); f1 = MFMA32(TM[1], lb[3], f1);
;             f32x16 f0 = MFMA32(TM[0], lb[0], X); f0 = MFMA32(TM[1], lb[1], f0);
;             C = MFMA32(JN, lb[0], X); C = MFMA32(JN, lb[1], C);
; #pragma unroll
;             for (int r = 0; r < 16; ++r) { y0[r] = __builtin_amdgcn_exp2f(y0[r] + f0[r]); y1[r] = __builtin_amdgcn_exp2f(y1[r] + f1[r]); }
;             bf16x8 pk[4]; pk[0] = pack8(y0, 0); pk[1] = pack8(y0, 8); pk[2] = pack8(y1, 0); pk[3] = pack8(y1, 8);
; #pragma unroll
;             for (int db = 0; db < 2; ++db)
; #pragma unroll
;                 for (int kk = 0; kk < 4; ++kk) { const bf16x8 vf = *(const LAS bf16x8*)(Vb + db * 4096 + vofs[kk]); o[db] = MFMA32(vf, pk[kk], o[db]); }
.LBB0_728:
	v_exp_f32_e32 v64, v0
	v_exp_f32_e32 v65, v2
	v_exp_f32_e32 v66, v3
	s_mov_b32 s70, s68
	v_add_f32_e32 v64, 1.0, v64
	v_log_f32_e32 v83, v64
	v_add_f32_e32 v64, 1.0, v65
	v_log_f32_e32 v92, v64
	v_exp_f32_e32 v64, v5
	v_add_f32_e32 v65, 1.0, v66
	v_log_f32_e32 v93, v65
	v_exp_f32_e32 v65, v4
	v_add_f32_e32 v64, 1.0, v64
	v_log_f32_e32 v94, v64
	v_exp_f32_e32 v64, v6
	v_add_f32_e32 v65, 1.0, v65
	v_log_f32_e32 v95, v65
	v_exp_f32_e32 v65, v7
	v_add_f32_e32 v64, 1.0, v64
	v_log_f32_e32 v184, v64
	v_exp_f32_e32 v64, v8
	v_add_f32_e32 v65, 1.0, v65
	v_log_f32_e32 v185, v65
	v_exp_f32_e32 v65, v9
	v_add_f32_e32 v64, 1.0, v64
	v_log_f32_e32 v186, v64
	v_exp_f32_e32 v64, v10
	v_add_f32_e32 v65, 1.0, v65
	v_log_f32_e32 v187, v65
	v_exp_f32_e32 v65, v12
	v_add_f32_e32 v64, 1.0, v64
	v_log_f32_e32 v188, v64
	v_exp_f32_e32 v64, v11
	v_add_f32_e32 v65, 1.0, v65
	v_log_f32_e32 v189, v65
	v_exp_f32_e32 v65, v13
	v_add_f32_e32 v64, 1.0, v64
	v_log_f32_e32 v190, v64
	v_exp_f32_e32 v64, v14
	v_add_f32_e32 v65, 1.0, v65
	v_log_f32_e32 v191, v65
	v_exp_f32_e32 v65, v15
	v_add_f32_e32 v64, 1.0, v64
	v_log_f32_e32 v192, v64
	v_exp_f32_e32 v64, v80
	v_add_f32_e32 v65, 1.0, v65
	v_log_f32_e32 v193, v65
	v_exp_f32_e32 v65, v81
	v_add_f32_e32 v64, 1.0, v64
	v_log_f32_e32 v194, v64
	v_exp_f32_e32 v64, v82
	v_add_f32_e32 v65, 1.0, v65
	v_log_f32_e32 v195, v65
	v_exp_f32_e32 v65, v157
	v_add_f32_e32 v64, 1.0, v64
	v_log_f32_e32 v196, v64
	v_exp_f32_e32 v64, v158
	v_add_f32_e32 v65, 1.0, v65
	v_log_f32_e32 v197, v65
	v_exp_f32_e32 v65, v159
	v_add_f32_e32 v64, 1.0, v64
	v_log_f32_e32 v198, v64
	v_exp_f32_e32 v64, v160
	v_add_f32_e32 v65, 1.0, v65
	v_log_f32_e32 v199, v65
	v_exp_f32_e32 v65, v161
	v_add_f32_e32 v64, 1.0, v64
	v_log_f32_e32 v200, v64
	v_exp_f32_e32 v64, v162
	v_add_f32_e32 v65, 1.0, v65
	v_log_f32_e32 v201, v65
	v_exp_f32_e32 v65, v164
	v_add_f32_e32 v64, 1.0, v64
	v_log_f32_e32 v202, v64
	v_exp_f32_e32 v64, v163
	v_add_f32_e32 v65, 1.0, v65
	v_log_f32_e32 v203, v65
	v_exp_f32_e32 v65, v165
	v_add_f32_e32 v64, 1.0, v64
	v_log_f32_e32 v204, v64
	v_exp_f32_e32 v64, v166
	v_add_f32_e32 v65, 1.0, v65
	v_log_f32_e32 v205, v65
	v_exp_f32_e32 v65, v167
	v_add_f32_e32 v64, 1.0, v64
	v_log_f32_e32 v206, v64
	v_exp_f32_e32 v64, v168
	v_add_f32_e32 v65, 1.0, v65
	s_mov_b32 s71, s68
	v_add_u32_e32 v171, s69, v155
	v_log_f32_e32 v207, v65
	v_exp_f32_e32 v65, v169
	s_mov_b32 s69, s68
	v_mov_b64_e32 v[178:179], s[70:71]
	v_exp_f32_e32 v66, v170
	v_mov_b64_e32 v[176:177], s[68:69]
	v_add_f32_e32 v64, 1.0, v64
	v_log_f32_e32 v208, v64
	v_add_f32_e32 v64, 1.0, v65
	v_log_f32_e32 v209, v64
	v_add_f32_e32 v64, 1.0, v66
	v_cvt_pk_bf16_f32 v84, v92, v94
	v_cvt_pk_bf16_f32 v85, v184, v186
	v_cvt_pk_bf16_f32 v86, v188, v190
	v_cvt_pk_bf16_f32 v87, v192, v194
	v_log_f32_e32 v210, v64
	v_cvt_pk_bf16_f32 v88, v196, v198
	v_mfma_f32_32x32x16_bf16 v[64:79], v[176:179], v[84:87], v[48:63]
	v_cvt_pk_bf16_f32 v89, v200, v202
	v_cvt_pk_bf16_f32 v90, v204, v206
	v_cvt_pk_bf16_f32 v91, v208, v210
	v_cvt_pk_bf16_f32 v172, v83, v93
	v_cvt_pk_bf16_f32 v173, v95, v185
	v_cvt_pk_bf16_f32 v174, v187, v189
	v_cvt_pk_bf16_f32 v175, v191, v193
	v_mfma_f32_32x32x16_bf16 v[64:79], v[176:179], v[88:91], v[64:79]
	v_sub_f32_e32 v0, v0, v83
	v_sub_f32_e32 v2, v2, v92
	v_sub_f32_e32 v3, v3, v93
	v_sub_f32_e32 v5, v5, v94
	v_sub_f32_e32 v4, v4, v95
	v_sub_f32_e32 v6, v6, v184
	v_sub_f32_e32 v7, v7, v185
	v_mfma_f32_32x32x16_bf16 v[48:63], v[96:99], v[84:87], v[48:63]
	v_sub_f32_e32 v8, v8, v186
	v_sub_f32_e32 v184, v80, v194
	v_sub_f32_e32 v185, v81, v195
	v_sub_f32_e32 v186, v82, v196
	v_cvt_pk_bf16_f32 v180, v195, v197
	v_cvt_pk_bf16_f32 v181, v199, v201
	v_cvt_pk_bf16_f32 v182, v203, v205
	v_mfma_f32_32x32x16_bf16 v[48:63], v[116:119], v[88:91], v[48:63]
	v_cvt_pk_bf16_f32 v183, v207, v209
	v_sub_f32_e32 v9, v9, v187
	v_sub_f32_e32 v10, v10, v188
	v_sub_f32_e32 v12, v12, v189
	v_sub_f32_e32 v11, v11, v190
	v_sub_f32_e32 v13, v13, v191
	v_sub_f32_e32 v14, v14, v192
	v_mfma_f32_32x32x16_bf16 v[80:95], v[96:99], v[172:175], v[64:79]
	s_nop 3
	v_add_f32_e32 v2, v2, v48
	v_sub_f32_e32 v15, v15, v193
	v_sub_f32_e32 v157, v157, v197
	v_sub_f32_e32 v158, v158, v198
	v_sub_f32_e32 v159, v159, v199
	v_sub_f32_e32 v160, v160, v200
	v_sub_f32_e32 v161, v161, v201
	v_mfma_f32_32x32x16_bf16 v[80:95], v[116:119], v[180:183], v[80:95]
	v_sub_f32_e32 v162, v162, v202
	v_sub_f32_e32 v164, v164, v203
	v_sub_f32_e32 v163, v163, v204
	v_sub_f32_e32 v165, v165, v205
	v_sub_f32_e32 v166, v166, v206
	v_sub_f32_e32 v167, v167, v207
	v_sub_f32_e32 v168, v168, v208
	s_nop 4
	v_add_f32_e32 v0, v0, v80
	v_exp_f32_e32 v80, v2
	v_add_f32_e32 v2, v3, v81
	v_exp_f32_e32 v48, v2
	v_add_f32_e32 v2, v5, v49
	v_exp_f32_e32 v81, v2
	v_add_f32_e32 v2, v4, v82
	v_exp_f32_e32 v49, v2
	v_add_f32_e32 v2, v6, v50
	v_exp_f32_e32 v82, v2
	v_add_f32_e32 v2, v7, v83
	v_exp_f32_e32 v7, v2
	v_add_f32_e32 v2, v8, v51
	v_exp_f32_e32 v83, v2
	v_add_f32_e32 v2, v9, v84
	v_exp_f32_e32 v8, v2
	v_add_f32_e32 v2, v10, v52
	v_exp_f32_e32 v84, v2
	v_add_f32_e32 v2, v12, v85
	v_exp_f32_e32 v9, v2
	v_add_f32_e32 v2, v11, v53
	v_exp_f32_e32 v85, v2
	v_add_f32_e32 v2, v13, v86
	v_exp_f32_e32 v10, v2
	v_add_f32_e32 v2, v14, v54
	v_exp_f32_e32 v14, v2
	v_add_f32_e32 v2, v15, v87
	v_exp_f32_e32 v11, v2
	v_add_f32_e32 v2, v184, v55
	v_exp_f32_e32 v15, v2
	v_add_f32_e32 v2, v185, v88
	v_exp_f32_e32 v52, v2
	v_add_f32_e32 v2, v186, v56
	v_exp_f32_e32 v88, v2
	v_add_f32_e32 v2, v157, v89
	v_exp_f32_e32 v53, v2
	v_add_f32_e32 v2, v158, v57
	v_exp_f32_e32 v89, v2
	v_add_f32_e32 v2, v159, v90
	v_exp_f32_e32 v54, v2
	v_add_f32_e32 v2, v160, v58
	v_exp_f32_e32 v90, v2
	v_add_f32_e32 v2, v161, v91
	v_exp_f32_e32 v55, v2
	v_add_f32_e32 v2, v162, v59
	v_exp_f32_e32 v91, v2
	v_add_f32_e32 v2, v164, v92
	v_exp_f32_e32 v56, v2
	v_add_f32_e32 v2, v163, v60
	v_exp_f32_e32 v60, v2
	v_add_f32_e32 v2, v165, v93
	v_exp_f32_e32 v57, v2
	v_add_f32_e32 v2, v166, v61
	v_exp_f32_e32 v61, v2
	v_add_f32_e32 v2, v167, v94
	v_exp_f32_e32 v58, v2
	v_add_f32_e32 v2, v168, v62
	v_add_u32_e32 v50, v171, v147
	v_exp_f32_e32 v0, v0
	v_exp_f32_e32 v62, v2
	v_sub_f32_e32 v169, v169, v209
	v_add_f32_e32 v6, v169, v95
	v_exp_f32_e32 v59, v6
	v_cvt_pk_bf16_f32 v6, v0, v48
	v_add_u32_e32 v0, v171, v149
	v_cvt_pk_bf16_f32 v7, v49, v7
	v_cvt_pk_bf16_f32 v8, v8, v9
	v_cvt_pk_bf16_f32 v9, v10, v11
	s_waitcnt lgkmcnt(2)
; #define LAS __attribute__((address_space(3)))
; #define MFMA32(a, b, c) __builtin_amdgcn_mfma_f32_32x32x16_bf16((a), (b), (c), 0, 0, 0)
; __device__ __forceinline__ void sb_unit(int b, int h, int qb, const bf16* U, const bf16* VT, bf16* Y, unsigned char* lds, int wid, int lane, int& res_lo, int& res_hi) {
;     ...
;             f32x16 f0 = MFMA32(TM[0], lb[0], X); f0 = MFMA32(TM[1], lb[1], f0);
;             C = MFMA32(JN, lb[0], X); C = MFMA32(JN, lb[1], C);
; #pragma unroll
;             for (int r = 0; r < 16; ++r) { y0[r] = __builtin_amdgcn_exp2f(y0[r] + f0[r]); y1[r] = __builtin_amdgcn_exp2f(y1[r] + f1[r]); }
;             bf16x8 pk[4]; pk[0] = pack8(y0, 0); pk[1] = pack8(y0, 8); pk[2] = pack8(y1, 0); pk[3] = pack8(y1, 8);
; #pragma unroll
;             for (int db = 0; db < 2; ++db)
; #pragma unroll
;                 for (int kk = 0; kk < 4; ++kk) { const bf16x8 vf = *(const LAS bf16x8*)(Vb + db * 4096 + vofs[kk]); o[db] = MFMA32(vf, pk[kk], o[db]); }
;             alive = __any(C[0] > -160.f);
	v_mfma_f32_32x32x16_bf16 v[32:47], v[212:215], v[6:9], v[32:47]
	v_add_u32_e32 v86, v171, v151
	v_cvt_pk_bf16_f32 v2, v52, v53
	v_cvt_pk_bf16_f32 v3, v54, v55
	v_cvt_pk_bf16_f32 v4, v56, v57
	v_cvt_pk_bf16_f32 v5, v58, v59
	v_sub_f32_e32 v170, v170, v210
	s_waitcnt lgkmcnt(2)
	v_mfma_f32_32x32x16_bf16 v[16:31], v[216:219], v[6:9], v[16:31]
	v_add_u32_e32 v0, v171, v153
	s_mov_b32 s2, 0xc3200000
	v_mfma_f32_32x32x16_bf16 v[32:47], v[220:223], v[2:5], v[32:47]
	v_cvt_pk_bf16_f32 v13, v14, v15
	v_add_f32_e32 v14, v170, v63
	v_cvt_pk_bf16_f32 v10, v80, v81
	v_cvt_pk_bf16_f32 v11, v82, v83
	v_cvt_pk_bf16_f32 v12, v84, v85
	v_exp_f32_e32 v14, v14
	s_waitcnt lgkmcnt(2)
	v_mfma_f32_32x32x16_bf16 v[16:31], v[224:227], v[2:5], v[16:31]
	v_mfma_f32_32x32x16_bf16 v[32:47], v[228:231], v[10:13], v[32:47]
	v_cvt_pk_bf16_f32 v54, v60, v61
	v_cvt_pk_bf16_f32 v55, v62, v14
	v_cvt_pk_bf16_f32 v52, v88, v89
	v_cvt_pk_bf16_f32 v53, v90, v91
	v_mfma_f32_32x32x16_bf16 v[64:79], v[176:179], v[172:175], v[64:79]
	s_waitcnt lgkmcnt(1)
	v_mfma_f32_32x32x16_bf16 v[16:31], v[232:235], v[10:13], v[16:31]
	v_mfma_f32_32x32x16_bf16 v[32:47], v[236:239], v[52:55], v[32:47]
	s_waitcnt lgkmcnt(0)
	v_mfma_f32_32x32x16_bf16 v[16:31], v[240:243], v[52:55], v[16:31]
	v_mfma_f32_32x32x16_bf16 v[48:63], v[176:179], v[180:183], v[64:79]
	s_add_i32 s70, s82, 0xffffc000
	s_and_b32 s70, s70, 0x1c000
	v_add_u32_e32 v0, s70, v154
	v_add_u32_e32 v6, v0, v146
	v_add_u32_e32 v10, v0, v148
	ds_read_b128 v[212:215], v6
	ds_read_b128 v[216:219], v6 offset:4096
	ds_read_b128 v[220:223], v10
	ds_read_b128 v[224:227], v10 offset:4096
	v_add_u32_e32 v10, v0, v150
	v_add_u32_e32 v0, v0, v152
	ds_read_b128 v[228:231], v10
	ds_read_b128 v[232:235], v10 offset:4096
	ds_read_b128 v[236:239], v0
	ds_read_b128 v[240:243], v0 offset:4096
	v_cmp_lt_f32_e32 vcc, s2, v48
	s_cmp_lg_u64 vcc, 0
	s_cselect_b64 s[2:3], -1, 0
	s_add_i32 s6, s89, -1
	s_cmp_gt_i32 s89, s87
	s_cselect_b64 s[8:9], -1, 0
	s_and_b64 s[8:9], s[8:9], s[2:3]
	s_andn2_b64 vcc, exec, s[8:9]
	s_addk_i32 s82, 0xc000
	s_cbranch_vccnz .LBB0_733
	s_mov_b32 s89, s6
	s_branch .LBB0_726
